# v16 + GEMM unit-order index math: runtime division by group size replaced by shifts (group size is always 8)
# baseline (speedup 1.0000x reference)
.LBB0_253:
	s_add_i32 s69, s69, 1
	s_mul_i32 s0, s69, s39
	s_mul_hi_u32 s4, s69, s16
	s_add_i32 s4, s4, s0
	s_mul_i32 s0, s69, s16
	s_add_u32 s20, s0, s2
	s_addc_u32 s21, s4, s17
	v_mov_b64_e32 v[2:3], s[22:23]
	v_cmp_ge_i64_e32 vcc, s[20:21], v[2:3]
	v_cmp_lt_i64_e64 s[4:5], s[20:21], v[2:3]
	s_cbranch_vccnz .LBB0_255
	s_ashr_i32 s0, s20, 31
	s_lshr_b32 s0, s0, 29
	s_add_i32 s0, s20, s0
	s_ashr_i32 s12, s0, 3
	s_and_b32 s0, s0, -8
	s_sub_i32 s0, s20, s0
	s_cmp_lt_i32 s0, 0
	s_cselect_b32 s13, s87, s86
	s_mul_i32 s0, s13, s0
	s_add_i32 s0, s0, s12
	s_mul_hi_i32 s12, s0, 0x2e8ba2e9
	s_lshr_b32 s13, s12, 31
	s_ashr_i32 s12, s12, 5
	s_add_i32 s12, s12, s13
	s_lshl_b32 s13, s12, 3
	s_mulk_i32 s12, 0xb0
	s_sub_i32 s0, s0, s12
	s_lshr_b32 s12, s0, 3
	s_and_b32 s0, s0, 7
	s_add_i32 s14, s0, s13

.LBB0_280:
	s_add_i32 s31, s31, 1
	s_mul_i32 s8, s31, s39
	s_mul_hi_u32 s9, s31, s16
	s_add_i32 s9, s9, s8
	s_mul_i32 s8, s31, s16
	s_add_u32 s20, s8, s2
	s_addc_u32 s21, s9, s17
	v_mov_b64_e32 v[2:3], 0x240
	v_cmp_lt_i64_e64 s[8:9], s[20:21], v[2:3]
	v_mov_b64_e32 v[2:3], 0x23f
	v_cmp_gt_i64_e32 vcc, s[20:21], v[2:3]
	s_cbranch_vccnz .LBB0_282
	s_ashr_i32 s21, s20, 31
	s_lshr_b32 s21, s21, 29
	s_add_i32 s21, s20, s21
	s_ashr_i32 s36, s21, 3
	s_and_b32 s21, s21, -8
	s_sub_i32 s20, s20, s21
	s_cmp_lt_i32 s20, 0
	s_movk_i32 s0, 0x49
	s_cselect_b32 s21, s0, 0x48
	s_mul_i32 s20, s20, s21
	s_add_i32 s20, s20, s36
	s_mul_hi_i32 s21, s20, 0x2aaaaaab
	s_lshr_b32 s36, s21, 31
	s_ashr_i32 s21, s21, 3
	s_add_i32 s21, s21, s36
	s_lshl_b32 s36, s21, 3
	s_mul_i32 s21, s21, 48
	s_sub_i32 s20, s20, s21
	s_lshr_b32 s56, s20, 3
	s_and_b32 s20, s20, 7
	s_add_i32 s58, s36, s20

.LBB0_664:
	s_add_i32 s86, s86, 1
	s_mul_i32 s0, s86, s39
	s_mul_hi_u32 s4, s86, s16
	s_add_i32 s0, s4, s0
	s_mul_i32 s4, s86, s16
	s_add_u32 s4, s4, s2
	s_addc_u32 s5, s0, s17
	s_waitcnt lgkmcnt(0)
	v_mov_b64_e32 v[2:3], s[24:25]
	v_cmp_ge_i64_e32 vcc, s[4:5], v[2:3]
	v_cmp_lt_i64_e64 s[6:7], s[4:5], v[2:3]
	s_cbranch_vccnz .LBB0_666
	s_ashr_i32 s0, s4, 31
	s_lshr_b32 s0, s0, 29
	s_add_i32 s0, s4, s0
	s_ashr_i32 s5, s0, 3
	s_and_b32 s0, s0, -8
	s_sub_i32 s0, s4, s0
	s_lshr_b32 s4, s0, 31
	v_readlane_b32 s13, v254, 40
	s_or_b32 s4, s13, s4
	s_mul_i32 s0, s4, s0
	s_add_i32 s0, s0, s5
	s_ashr_i32 s4, s0, 31
	s_lshr_b32 s4, s4, 27
	s_add_i32 s4, s0, s4
	s_ashr_i32 s5, s4, 5
	s_lshl_b32 s5, s5, 3
	s_andn2_b32 s4, s4, 31
	s_sub_i32 s0, s0, s4
	s_lshr_b32 s13, s0, 3
	s_and_b32 s0, s0, 7
	s_add_i32 s87, s0, s5
